# k13 plus: hand-written SwiGLU epilogues for both gate-up GEMMs (packed f32 math, row statistics read up front, ~40 percent fewer VALU instructions)
# speedup vs baseline: 1.0135x; 1.0135x over previous
; __device__ __forceinline__ float rstd_of(float ss, float inv_n) { return __builtin_amdgcn_rsqf(ss * inv_n + 1e-6f); }
; __device__ __forceinline__ float sigmoid_f(float v) { return __builtin_amdgcn_rcpf(1.0f + __builtin_amdgcn_exp2f(-1.4426950408889634f * v)); }
; __device__ __forceinline__ u32x4 pack8(const f32x4 a, const f32x4 b) { u32x4 w; w.x = cvt_pk_bf16(a[0], a[1]); w.y = cvt_pk_bf16(a[2], a[3]); w.z = cvt_pk_bf16(b[0], b[1]); w.w = cvt_pk_bf16(b[2], b[3]); return w; }
;     __device__ __forceinline__ void operator()(f32x4 (&acc)[2][2][4][2], const Unit& u_, int wr, int wc, int fr, int fq) const {
;         Unit u = u_; if constexpr (OPQ) { unsigned o1_ = ~0u; asm volatile("" : "+s"(u.pm), "+s"(u.pn), "+s"(o1_)); const int l_ = (int)__builtin_amdgcn_mbcnt_hi(o1_, __builtin_amdgcn_mbcnt_lo(o1_, 0u)); fr = l_ & 15; fq = l_ >> 4; }
;         const int row0 = u.pm * BM + wr * 64 + fr, col0 = u.pn * HALF + wc * 32 + 8 * fq;
; #pragma unroll
;         for (int ai = 0; ai < 2; ++ai)
; #pragma unroll
;             for (int m = 0; m < 4; ++m) {
;                 const int row = row0 + ai * HALF + m * 16; const float r = rstd_of(sl[u.par * 256 + ai * HALF + wr * 64 + m * 16 + fr], 1.0f / 2048.0f) * ascale;
;                 f32x4 o[2];
; #pragma unroll
;                 for (int n = 0; n < 2; ++n) { const f32x4 g = acc[ai][0][m][n] * r, uu = acc[ai][1][m][n] * r;
; #pragma unroll
;                     for (int e = 0; e < 4; ++e) o[n][e] = g[e] * uu[e] * sigmoid_f(g[e]); }
;                 if constexpr (F8OUT) {
;                     typedef unsigned u32x2 __attribute__((ext_vector_type(2))); u32x2 w8; w8.x = pack4_fp8(o[0][0] * F8_ACT_SCALE, o[0][1] * F8_ACT_SCALE, o[0][2] * F8_ACT_SCALE, o[0][3] * F8_ACT_SCALE);
;                     w8.y = pack4_fp8(o[1][0] * F8_ACT_SCALE, o[1][1] * F8_ACT_SCALE, o[1][2] * F8_ACT_SCALE, o[1][3] * F8_ACT_SCALE);
;                     *(u32x2*)((unsigned char*)O + (((size_t)u.pm * (ldo / 128) + (col0 >> 7)) * BM + (ai * HALF + wr * 64 + m * 16 + fr)) * 128 + (col0 & 127)) = w8;
;                 } else
;                 *(u32x4*)(O + (((size_t)u.pm * (ldo / 64) + (col0 >> 6)) * BM + (ai * HALF + wr * 64 + m * 16 + fr)) * 64 + (col0 & 63)) = pack8(o[0], o[1]);
;             }
;     }
.LBB0_228:
	v_lshl_add_u32 v166, s76, 10, v162
	ds_read_b32 v172, v166
	ds_read_b32 v173, v166 offset:64
	ds_read_b32 v174, v166 offset:128
	ds_read_b32 v175, v166 offset:192
	ds_read_b32 v176, v166 offset:512
	ds_read_b32 v177, v166 offset:576
	ds_read_b32 v178, v166 offset:640
	ds_read_b32 v179, v166 offset:704
	v_lshl_add_u32 v167, s56, 7, v161
	s_andn2_b64 vcc, exec, s[6:7]
	s_mov_b64 s[6:7], -1
	v_ashrrev_i32_e32 v168, 6, v167
	v_ashrrev_i32_e32 v169, 31, v168
	v_mad_i64_i32 v[180:181], s[8:9], s54, v165, v[168:169]
	v_mov_b32_e32 v170, v152
	v_mov_b32_e32 v171, v129
	v_lshlrev_b64 v[180:181], 15, v[180:181]
	v_mov_b32_e32 v182, 1.0
	v_lshl_add_u64 v[180:181], s[34:35], 0, v[180:181]
	v_lshl_add_u64 v[180:181], v[180:181], 0, v[170:171]
	s_waitcnt lgkmcnt(0)
	v_fmamk_f32 v184, v172, 0x3a000000, v164
	v_rsq_f32_e32 v184, v184
	v_lshl_add_u64 v[202:203], v[180:181], 0, v[130:131]
	v_mul_f32_e32 v186, 0xbfb8aa3b, v184
	v_mul_f32_e32 v188, v184, v184
	v_pk_mul_f32 v[190:191], v[124:125], v[186:187] op_sel_hi:[1,0]
	v_pk_mul_f32 v[192:193], v[126:127], v[186:187] op_sel_hi:[1,0]
	v_pk_mul_f32 v[124:125], v[124:125], v[120:121]
	v_exp_f32_e32 v190, v190
	v_exp_f32_e32 v191, v191
	v_exp_f32_e32 v192, v192
	v_exp_f32_e32 v193, v193
	v_pk_mul_f32 v[126:127], v[126:127], v[122:123]
	v_pk_add_f32 v[190:191], v[190:191], v[182:183] op_sel_hi:[1,0]
	v_pk_add_f32 v[192:193], v[192:193], v[182:183] op_sel_hi:[1,0]
	v_pk_mul_f32 v[124:125], v[124:125], v[188:189] op_sel_hi:[1,0]
	v_rcp_f32_e32 v190, v190
	v_rcp_f32_e32 v191, v191
	v_rcp_f32_e32 v192, v192
	v_rcp_f32_e32 v193, v193
	v_pk_mul_f32 v[126:127], v[126:127], v[188:189] op_sel_hi:[1,0]
	v_pk_mul_f32 v[124:125], v[124:125], v[190:191]
	v_pk_mul_f32 v[126:127], v[126:127], v[192:193]
	v_pk_mul_f32 v[190:191], v[116:117], v[186:187] op_sel_hi:[1,0]
	v_pk_mul_f32 v[192:193], v[118:119], v[186:187] op_sel_hi:[1,0]
	v_pk_mul_f32 v[116:117], v[116:117], v[112:113]
	v_exp_f32_e32 v190, v190
	v_exp_f32_e32 v191, v191
	v_exp_f32_e32 v192, v192
	v_exp_f32_e32 v193, v193
	v_pk_mul_f32 v[118:119], v[118:119], v[114:115]
	v_pk_add_f32 v[190:191], v[190:191], v[182:183] op_sel_hi:[1,0]
	v_pk_add_f32 v[192:193], v[192:193], v[182:183] op_sel_hi:[1,0]
	v_pk_mul_f32 v[116:117], v[116:117], v[188:189] op_sel_hi:[1,0]
	v_rcp_f32_e32 v190, v190
	v_rcp_f32_e32 v191, v191
	v_rcp_f32_e32 v192, v192
	v_rcp_f32_e32 v193, v193
	v_pk_mul_f32 v[118:119], v[118:119], v[188:189] op_sel_hi:[1,0]
	v_pk_mul_f32 v[116:117], v[116:117], v[190:191]
	v_pk_mul_f32 v[118:119], v[118:119], v[192:193]
	v_cvt_pk_bf16_f32 v194, v124, v125
	v_cvt_pk_bf16_f32 v195, v126, v127
	v_cvt_pk_bf16_f32 v196, v116, v117
	v_cvt_pk_bf16_f32 v197, v118, v119
	global_store_dwordx4 v[202:203], v[194:197], off
	v_fmamk_f32 v184, v173, 0x3a000000, v164
	v_rsq_f32_e32 v184, v184
	v_lshl_add_u64 v[202:203], v[180:181], 0, v[132:133]
	v_mul_f32_e32 v186, 0xbfb8aa3b, v184
	v_mul_f32_e32 v188, v184, v184
	v_pk_mul_f32 v[190:191], v[108:109], v[186:187] op_sel_hi:[1,0]
	v_pk_mul_f32 v[192:193], v[110:111], v[186:187] op_sel_hi:[1,0]
	v_pk_mul_f32 v[108:109], v[108:109], v[104:105]
	v_exp_f32_e32 v190, v190
	v_exp_f32_e32 v191, v191
	v_exp_f32_e32 v192, v192
	v_exp_f32_e32 v193, v193
	v_pk_mul_f32 v[110:111], v[110:111], v[106:107]
	v_pk_add_f32 v[190:191], v[190:191], v[182:183] op_sel_hi:[1,0]
	v_pk_add_f32 v[192:193], v[192:193], v[182:183] op_sel_hi:[1,0]
	v_pk_mul_f32 v[108:109], v[108:109], v[188:189] op_sel_hi:[1,0]
	v_rcp_f32_e32 v190, v190
	v_rcp_f32_e32 v191, v191
	v_rcp_f32_e32 v192, v192
	v_rcp_f32_e32 v193, v193
	v_pk_mul_f32 v[110:111], v[110:111], v[188:189] op_sel_hi:[1,0]
	v_pk_mul_f32 v[108:109], v[108:109], v[190:191]
	v_pk_mul_f32 v[110:111], v[110:111], v[192:193]
	v_pk_mul_f32 v[190:191], v[100:101], v[186:187] op_sel_hi:[1,0]
	v_pk_mul_f32 v[192:193], v[102:103], v[186:187] op_sel_hi:[1,0]
	v_pk_mul_f32 v[100:101], v[100:101], v[96:97]
	v_exp_f32_e32 v190, v190
	v_exp_f32_e32 v191, v191
	v_exp_f32_e32 v192, v192
	v_exp_f32_e32 v193, v193
	v_pk_mul_f32 v[102:103], v[102:103], v[98:99]
	v_pk_add_f32 v[190:191], v[190:191], v[182:183] op_sel_hi:[1,0]
	v_pk_add_f32 v[192:193], v[192:193], v[182:183] op_sel_hi:[1,0]
	v_pk_mul_f32 v[100:101], v[100:101], v[188:189] op_sel_hi:[1,0]
	v_rcp_f32_e32 v190, v190
	v_rcp_f32_e32 v191, v191
	v_rcp_f32_e32 v192, v192
	v_rcp_f32_e32 v193, v193
	v_pk_mul_f32 v[102:103], v[102:103], v[188:189] op_sel_hi:[1,0]
	v_pk_mul_f32 v[100:101], v[100:101], v[190:191]
	v_pk_mul_f32 v[102:103], v[102:103], v[192:193]
	v_cvt_pk_bf16_f32 v198, v108, v109
	v_cvt_pk_bf16_f32 v199, v110, v111
	v_cvt_pk_bf16_f32 v200, v100, v101
	v_cvt_pk_bf16_f32 v201, v102, v103
	global_store_dwordx4 v[202:203], v[198:201], off
	v_fmamk_f32 v184, v174, 0x3a000000, v164
	v_rsq_f32_e32 v184, v184
	v_lshl_add_u64 v[202:203], v[180:181], 0, v[134:135]
	v_mul_f32_e32 v186, 0xbfb8aa3b, v184
	v_mul_f32_e32 v188, v184, v184
	v_pk_mul_f32 v[190:191], v[92:93], v[186:187] op_sel_hi:[1,0]
	v_pk_mul_f32 v[192:193], v[94:95], v[186:187] op_sel_hi:[1,0]
	v_pk_mul_f32 v[92:93], v[92:93], v[88:89]
	v_exp_f32_e32 v190, v190
	v_exp_f32_e32 v191, v191
	v_exp_f32_e32 v192, v192
	v_exp_f32_e32 v193, v193
	v_pk_mul_f32 v[94:95], v[94:95], v[90:91]
	v_pk_add_f32 v[190:191], v[190:191], v[182:183] op_sel_hi:[1,0]
	v_pk_add_f32 v[192:193], v[192:193], v[182:183] op_sel_hi:[1,0]
	v_pk_mul_f32 v[92:93], v[92:93], v[188:189] op_sel_hi:[1,0]
	v_rcp_f32_e32 v190, v190
	v_rcp_f32_e32 v191, v191
	v_rcp_f32_e32 v192, v192
	v_rcp_f32_e32 v193, v193
	v_pk_mul_f32 v[94:95], v[94:95], v[188:189] op_sel_hi:[1,0]
	v_pk_mul_f32 v[92:93], v[92:93], v[190:191]
; __device__ __forceinline__ float rstd_of(float ss, float inv_n) { return __builtin_amdgcn_rsqf(ss * inv_n + 1e-6f); }
; __device__ __forceinline__ float sigmoid_f(float v) { return __builtin_amdgcn_rcpf(1.0f + __builtin_amdgcn_exp2f(-1.4426950408889634f * v)); }
; __device__ __forceinline__ u32x4 pack8(const f32x4 a, const f32x4 b) { u32x4 w; w.x = cvt_pk_bf16(a[0], a[1]); w.y = cvt_pk_bf16(a[2], a[3]); w.z = cvt_pk_bf16(b[0], b[1]); w.w = cvt_pk_bf16(b[2], b[3]); return w; }
;     __device__ __forceinline__ void operator()(f32x4 (&acc)[2][2][4][2], const Unit& u_, int wr, int wc, int fr, int fq) const {
;         Unit u = u_; if constexpr (OPQ) { unsigned o1_ = ~0u; asm volatile("" : "+s"(u.pm), "+s"(u.pn), "+s"(o1_)); const int l_ = (int)__builtin_amdgcn_mbcnt_hi(o1_, __builtin_amdgcn_mbcnt_lo(o1_, 0u)); fr = l_ & 15; fq = l_ >> 4; }
;         const int row0 = u.pm * BM + wr * 64 + fr, col0 = u.pn * HALF + wc * 32 + 8 * fq;
; #pragma unroll
;         for (int ai = 0; ai < 2; ++ai)
; #pragma unroll
;             for (int m = 0; m < 4; ++m) {
;                 const int row = row0 + ai * HALF + m * 16; const float r = rstd_of(sl[u.par * 256 + ai * HALF + wr * 64 + m * 16 + fr], 1.0f / 2048.0f) * ascale;
;                 f32x4 o[2];
; #pragma unroll
;                 for (int n = 0; n < 2; ++n) { const f32x4 g = acc[ai][0][m][n] * r, uu = acc[ai][1][m][n] * r;
; #pragma unroll
;                     for (int e = 0; e < 4; ++e) o[n][e] = g[e] * uu[e] * sigmoid_f(g[e]); }
;                 if constexpr (F8OUT) {
;                     typedef unsigned u32x2 __attribute__((ext_vector_type(2))); u32x2 w8; w8.x = pack4_fp8(o[0][0] * F8_ACT_SCALE, o[0][1] * F8_ACT_SCALE, o[0][2] * F8_ACT_SCALE, o[0][3] * F8_ACT_SCALE);
;                     w8.y = pack4_fp8(o[1][0] * F8_ACT_SCALE, o[1][1] * F8_ACT_SCALE, o[1][2] * F8_ACT_SCALE, o[1][3] * F8_ACT_SCALE);
;                     *(u32x2*)((unsigned char*)O + (((size_t)u.pm * (ldo / 128) + (col0 >> 7)) * BM + (ai * HALF + wr * 64 + m * 16 + fr)) * 128 + (col0 & 127)) = w8;
;                 } else
;                 *(u32x4*)(O + (((size_t)u.pm * (ldo / 64) + (col0 >> 6)) * BM + (ai * HALF + wr * 64 + m * 16 + fr)) * 64 + (col0 & 63)) = pack8(o[0], o[1]);
;             }
;     }
	v_pk_mul_f32 v[94:95], v[94:95], v[192:193]
	v_pk_mul_f32 v[190:191], v[84:85], v[186:187] op_sel_hi:[1,0]
	v_pk_mul_f32 v[192:193], v[86:87], v[186:187] op_sel_hi:[1,0]
	v_pk_mul_f32 v[84:85], v[84:85], v[80:81]
	v_exp_f32_e32 v190, v190
	v_exp_f32_e32 v191, v191
	v_exp_f32_e32 v192, v192
	v_exp_f32_e32 v193, v193
	v_pk_mul_f32 v[86:87], v[86:87], v[82:83]
	v_pk_add_f32 v[190:191], v[190:191], v[182:183] op_sel_hi:[1,0]
	v_pk_add_f32 v[192:193], v[192:193], v[182:183] op_sel_hi:[1,0]
	v_pk_mul_f32 v[84:85], v[84:85], v[188:189] op_sel_hi:[1,0]
	v_rcp_f32_e32 v190, v190
	v_rcp_f32_e32 v191, v191
	v_rcp_f32_e32 v192, v192
	v_rcp_f32_e32 v193, v193
	v_pk_mul_f32 v[86:87], v[86:87], v[188:189] op_sel_hi:[1,0]
	v_pk_mul_f32 v[84:85], v[84:85], v[190:191]
	v_pk_mul_f32 v[86:87], v[86:87], v[192:193]
	v_cvt_pk_bf16_f32 v194, v92, v93
	v_cvt_pk_bf16_f32 v195, v94, v95
	v_cvt_pk_bf16_f32 v196, v84, v85
	v_cvt_pk_bf16_f32 v197, v86, v87
	global_store_dwordx4 v[202:203], v[194:197], off
	v_fmamk_f32 v184, v175, 0x3a000000, v164
	v_rsq_f32_e32 v184, v184
	v_lshl_add_u64 v[202:203], v[180:181], 0, v[136:137]
	v_mul_f32_e32 v186, 0xbfb8aa3b, v184
	v_mul_f32_e32 v188, v184, v184
	v_pk_mul_f32 v[190:191], v[76:77], v[186:187] op_sel_hi:[1,0]
	v_pk_mul_f32 v[192:193], v[78:79], v[186:187] op_sel_hi:[1,0]
	v_pk_mul_f32 v[76:77], v[76:77], v[72:73]
	v_exp_f32_e32 v190, v190
	v_exp_f32_e32 v191, v191
	v_exp_f32_e32 v192, v192
	v_exp_f32_e32 v193, v193
	v_pk_mul_f32 v[78:79], v[78:79], v[74:75]
	v_pk_add_f32 v[190:191], v[190:191], v[182:183] op_sel_hi:[1,0]
	v_pk_add_f32 v[192:193], v[192:193], v[182:183] op_sel_hi:[1,0]
	v_pk_mul_f32 v[76:77], v[76:77], v[188:189] op_sel_hi:[1,0]
	v_rcp_f32_e32 v190, v190
	v_rcp_f32_e32 v191, v191
	v_rcp_f32_e32 v192, v192
	v_rcp_f32_e32 v193, v193
	v_pk_mul_f32 v[78:79], v[78:79], v[188:189] op_sel_hi:[1,0]
	v_pk_mul_f32 v[76:77], v[76:77], v[190:191]
	v_pk_mul_f32 v[78:79], v[78:79], v[192:193]
	v_pk_mul_f32 v[190:191], v[68:69], v[186:187] op_sel_hi:[1,0]
	v_pk_mul_f32 v[192:193], v[70:71], v[186:187] op_sel_hi:[1,0]
	v_pk_mul_f32 v[68:69], v[68:69], v[64:65]
	v_exp_f32_e32 v190, v190
	v_exp_f32_e32 v191, v191
	v_exp_f32_e32 v192, v192
	v_exp_f32_e32 v193, v193
	v_pk_mul_f32 v[70:71], v[70:71], v[66:67]
	v_pk_add_f32 v[190:191], v[190:191], v[182:183] op_sel_hi:[1,0]
	v_pk_add_f32 v[192:193], v[192:193], v[182:183] op_sel_hi:[1,0]
	v_pk_mul_f32 v[68:69], v[68:69], v[188:189] op_sel_hi:[1,0]
	v_rcp_f32_e32 v190, v190
	v_rcp_f32_e32 v191, v191
	v_rcp_f32_e32 v192, v192
	v_rcp_f32_e32 v193, v193
	v_pk_mul_f32 v[70:71], v[70:71], v[188:189] op_sel_hi:[1,0]
	v_pk_mul_f32 v[68:69], v[68:69], v[190:191]
	v_pk_mul_f32 v[70:71], v[70:71], v[192:193]
	v_cvt_pk_bf16_f32 v198, v76, v77
	v_cvt_pk_bf16_f32 v199, v78, v79
	v_cvt_pk_bf16_f32 v200, v68, v69
	v_cvt_pk_bf16_f32 v201, v70, v71
	global_store_dwordx4 v[202:203], v[198:201], off
	v_fmamk_f32 v184, v176, 0x3a000000, v164
	v_rsq_f32_e32 v184, v184
	v_lshl_add_u64 v[202:203], v[180:181], 0, v[138:139]
	v_mul_f32_e32 v186, 0xbfb8aa3b, v184
	v_mul_f32_e32 v188, v184, v184
	v_pk_mul_f32 v[190:191], v[60:61], v[186:187] op_sel_hi:[1,0]
	v_pk_mul_f32 v[192:193], v[62:63], v[186:187] op_sel_hi:[1,0]
	v_pk_mul_f32 v[60:61], v[60:61], v[56:57]
	v_exp_f32_e32 v190, v190
	v_exp_f32_e32 v191, v191
	v_exp_f32_e32 v192, v192
	v_exp_f32_e32 v193, v193
	v_pk_mul_f32 v[62:63], v[62:63], v[58:59]
	v_pk_add_f32 v[190:191], v[190:191], v[182:183] op_sel_hi:[1,0]
	v_pk_add_f32 v[192:193], v[192:193], v[182:183] op_sel_hi:[1,0]
	v_pk_mul_f32 v[60:61], v[60:61], v[188:189] op_sel_hi:[1,0]
	v_rcp_f32_e32 v190, v190
	v_rcp_f32_e32 v191, v191
	v_rcp_f32_e32 v192, v192
	v_rcp_f32_e32 v193, v193
	v_pk_mul_f32 v[62:63], v[62:63], v[188:189] op_sel_hi:[1,0]
	v_pk_mul_f32 v[60:61], v[60:61], v[190:191]
	v_pk_mul_f32 v[62:63], v[62:63], v[192:193]
	v_pk_mul_f32 v[190:191], v[52:53], v[186:187] op_sel_hi:[1,0]
	v_pk_mul_f32 v[192:193], v[54:55], v[186:187] op_sel_hi:[1,0]
	v_pk_mul_f32 v[52:53], v[52:53], v[48:49]
	v_exp_f32_e32 v190, v190
	v_exp_f32_e32 v191, v191
	v_exp_f32_e32 v192, v192
	v_exp_f32_e32 v193, v193
	v_pk_mul_f32 v[54:55], v[54:55], v[50:51]
	v_pk_add_f32 v[190:191], v[190:191], v[182:183] op_sel_hi:[1,0]
	v_pk_add_f32 v[192:193], v[192:193], v[182:183] op_sel_hi:[1,0]
	v_pk_mul_f32 v[52:53], v[52:53], v[188:189] op_sel_hi:[1,0]
	v_rcp_f32_e32 v190, v190
	v_rcp_f32_e32 v191, v191
	v_rcp_f32_e32 v192, v192
	v_rcp_f32_e32 v193, v193
	v_pk_mul_f32 v[54:55], v[54:55], v[188:189] op_sel_hi:[1,0]
	v_pk_mul_f32 v[52:53], v[52:53], v[190:191]
	v_pk_mul_f32 v[54:55], v[54:55], v[192:193]
	v_cvt_pk_bf16_f32 v194, v60, v61
	v_cvt_pk_bf16_f32 v195, v62, v63
	v_cvt_pk_bf16_f32 v196, v52, v53
	v_cvt_pk_bf16_f32 v197, v54, v55
	global_store_dwordx4 v[202:203], v[194:197], off
	v_fmamk_f32 v184, v177, 0x3a000000, v164
	v_rsq_f32_e32 v184, v184
	v_lshl_add_u64 v[202:203], v[180:181], 0, v[140:141]
	v_mul_f32_e32 v186, 0xbfb8aa3b, v184
	v_mul_f32_e32 v188, v184, v184
	v_pk_mul_f32 v[190:191], v[44:45], v[186:187] op_sel_hi:[1,0]
	v_pk_mul_f32 v[192:193], v[46:47], v[186:187] op_sel_hi:[1,0]
	v_pk_mul_f32 v[44:45], v[44:45], v[40:41]
	v_exp_f32_e32 v190, v190
	v_exp_f32_e32 v191, v191
	v_exp_f32_e32 v192, v192
	v_exp_f32_e32 v193, v193
	v_pk_mul_f32 v[46:47], v[46:47], v[42:43]
; __device__ __forceinline__ float rstd_of(float ss, float inv_n) { return __builtin_amdgcn_rsqf(ss * inv_n + 1e-6f); }
; __device__ __forceinline__ float sigmoid_f(float v) { return __builtin_amdgcn_rcpf(1.0f + __builtin_amdgcn_exp2f(-1.4426950408889634f * v)); }
; __device__ __forceinline__ u32x4 pack8(const f32x4 a, const f32x4 b) { u32x4 w; w.x = cvt_pk_bf16(a[0], a[1]); w.y = cvt_pk_bf16(a[2], a[3]); w.z = cvt_pk_bf16(b[0], b[1]); w.w = cvt_pk_bf16(b[2], b[3]); return w; }
;     __device__ __forceinline__ void operator()(f32x4 (&acc)[2][2][4][2], const Unit& u_, int wr, int wc, int fr, int fq) const {
;         Unit u = u_; if constexpr (OPQ) { unsigned o1_ = ~0u; asm volatile("" : "+s"(u.pm), "+s"(u.pn), "+s"(o1_)); const int l_ = (int)__builtin_amdgcn_mbcnt_hi(o1_, __builtin_amdgcn_mbcnt_lo(o1_, 0u)); fr = l_ & 15; fq = l_ >> 4; }
;         const int row0 = u.pm * BM + wr * 64 + fr, col0 = u.pn * HALF + wc * 32 + 8 * fq;
; #pragma unroll
;         for (int ai = 0; ai < 2; ++ai)
; #pragma unroll
;             for (int m = 0; m < 4; ++m) {
;                 const int row = row0 + ai * HALF + m * 16; const float r = rstd_of(sl[u.par * 256 + ai * HALF + wr * 64 + m * 16 + fr], 1.0f / 2048.0f) * ascale;
;                 f32x4 o[2];
; #pragma unroll
;                 for (int n = 0; n < 2; ++n) { const f32x4 g = acc[ai][0][m][n] * r, uu = acc[ai][1][m][n] * r;
; #pragma unroll
;                     for (int e = 0; e < 4; ++e) o[n][e] = g[e] * uu[e] * sigmoid_f(g[e]); }
;                 if constexpr (F8OUT) {
;                     typedef unsigned u32x2 __attribute__((ext_vector_type(2))); u32x2 w8; w8.x = pack4_fp8(o[0][0] * F8_ACT_SCALE, o[0][1] * F8_ACT_SCALE, o[0][2] * F8_ACT_SCALE, o[0][3] * F8_ACT_SCALE);
;                     w8.y = pack4_fp8(o[1][0] * F8_ACT_SCALE, o[1][1] * F8_ACT_SCALE, o[1][2] * F8_ACT_SCALE, o[1][3] * F8_ACT_SCALE);
;                     *(u32x2*)((unsigned char*)O + (((size_t)u.pm * (ldo / 128) + (col0 >> 7)) * BM + (ai * HALF + wr * 64 + m * 16 + fr)) * 128 + (col0 & 127)) = w8;
;                 } else
;                 *(u32x4*)(O + (((size_t)u.pm * (ldo / 64) + (col0 >> 6)) * BM + (ai * HALF + wr * 64 + m * 16 + fr)) * 64 + (col0 & 63)) = pack8(o[0], o[1]);
;             }
;     }
	v_pk_add_f32 v[190:191], v[190:191], v[182:183] op_sel_hi:[1,0]
	v_pk_add_f32 v[192:193], v[192:193], v[182:183] op_sel_hi:[1,0]
	v_pk_mul_f32 v[44:45], v[44:45], v[188:189] op_sel_hi:[1,0]
	v_rcp_f32_e32 v190, v190
	v_rcp_f32_e32 v191, v191
	v_rcp_f32_e32 v192, v192
	v_rcp_f32_e32 v193, v193
	v_pk_mul_f32 v[46:47], v[46:47], v[188:189] op_sel_hi:[1,0]
	v_pk_mul_f32 v[44:45], v[44:45], v[190:191]
	v_pk_mul_f32 v[46:47], v[46:47], v[192:193]
	v_pk_mul_f32 v[190:191], v[36:37], v[186:187] op_sel_hi:[1,0]
	v_pk_mul_f32 v[192:193], v[38:39], v[186:187] op_sel_hi:[1,0]
	v_pk_mul_f32 v[36:37], v[36:37], v[32:33]
	v_exp_f32_e32 v190, v190
	v_exp_f32_e32 v191, v191
	v_exp_f32_e32 v192, v192
	v_exp_f32_e32 v193, v193
	v_pk_mul_f32 v[38:39], v[38:39], v[34:35]
	v_pk_add_f32 v[190:191], v[190:191], v[182:183] op_sel_hi:[1,0]
	v_pk_add_f32 v[192:193], v[192:193], v[182:183] op_sel_hi:[1,0]
	v_pk_mul_f32 v[36:37], v[36:37], v[188:189] op_sel_hi:[1,0]
	v_rcp_f32_e32 v190, v190
	v_rcp_f32_e32 v191, v191
	v_rcp_f32_e32 v192, v192
	v_rcp_f32_e32 v193, v193
	v_pk_mul_f32 v[38:39], v[38:39], v[188:189] op_sel_hi:[1,0]
	v_pk_mul_f32 v[36:37], v[36:37], v[190:191]
	v_pk_mul_f32 v[38:39], v[38:39], v[192:193]
	v_cvt_pk_bf16_f32 v198, v44, v45
	v_cvt_pk_bf16_f32 v199, v46, v47
	v_cvt_pk_bf16_f32 v200, v36, v37
	v_cvt_pk_bf16_f32 v201, v38, v39
	global_store_dwordx4 v[202:203], v[198:201], off
	v_fmamk_f32 v184, v178, 0x3a000000, v164
	v_rsq_f32_e32 v184, v184
	v_lshl_add_u64 v[202:203], v[180:181], 0, v[142:143]
	v_mul_f32_e32 v186, 0xbfb8aa3b, v184
	v_mul_f32_e32 v188, v184, v184
	v_pk_mul_f32 v[190:191], v[28:29], v[186:187] op_sel_hi:[1,0]
	v_pk_mul_f32 v[192:193], v[30:31], v[186:187] op_sel_hi:[1,0]
	v_pk_mul_f32 v[28:29], v[28:29], v[24:25]
	v_exp_f32_e32 v190, v190
	v_exp_f32_e32 v191, v191
	v_exp_f32_e32 v192, v192
	v_exp_f32_e32 v193, v193
	v_pk_mul_f32 v[30:31], v[30:31], v[26:27]
	v_pk_add_f32 v[190:191], v[190:191], v[182:183] op_sel_hi:[1,0]
	v_pk_add_f32 v[192:193], v[192:193], v[182:183] op_sel_hi:[1,0]
	v_pk_mul_f32 v[28:29], v[28:29], v[188:189] op_sel_hi:[1,0]
	v_rcp_f32_e32 v190, v190
	v_rcp_f32_e32 v191, v191
	v_rcp_f32_e32 v192, v192
	v_rcp_f32_e32 v193, v193
	v_pk_mul_f32 v[30:31], v[30:31], v[188:189] op_sel_hi:[1,0]
	v_pk_mul_f32 v[28:29], v[28:29], v[190:191]
	v_pk_mul_f32 v[30:31], v[30:31], v[192:193]
	v_pk_mul_f32 v[190:191], v[20:21], v[186:187] op_sel_hi:[1,0]
	v_pk_mul_f32 v[192:193], v[22:23], v[186:187] op_sel_hi:[1,0]
	v_pk_mul_f32 v[20:21], v[20:21], v[16:17]
	v_exp_f32_e32 v190, v190
	v_exp_f32_e32 v191, v191
	v_exp_f32_e32 v192, v192
	v_exp_f32_e32 v193, v193
	v_pk_mul_f32 v[22:23], v[22:23], v[18:19]
	v_pk_add_f32 v[190:191], v[190:191], v[182:183] op_sel_hi:[1,0]
	v_pk_add_f32 v[192:193], v[192:193], v[182:183] op_sel_hi:[1,0]
	v_pk_mul_f32 v[20:21], v[20:21], v[188:189] op_sel_hi:[1,0]
	v_rcp_f32_e32 v190, v190
	v_rcp_f32_e32 v191, v191
	v_rcp_f32_e32 v192, v192
	v_rcp_f32_e32 v193, v193
	v_pk_mul_f32 v[22:23], v[22:23], v[188:189] op_sel_hi:[1,0]
	v_pk_mul_f32 v[20:21], v[20:21], v[190:191]
	v_pk_mul_f32 v[22:23], v[22:23], v[192:193]
	v_cvt_pk_bf16_f32 v194, v28, v29
	v_cvt_pk_bf16_f32 v195, v30, v31
	v_cvt_pk_bf16_f32 v196, v20, v21
	v_cvt_pk_bf16_f32 v197, v22, v23
	global_store_dwordx4 v[202:203], v[194:197], off
	v_fmamk_f32 v184, v179, 0x3a000000, v164
	v_rsq_f32_e32 v184, v184
	v_lshl_add_u64 v[202:203], v[180:181], 0, v[144:145]
	v_mul_f32_e32 v186, 0xbfb8aa3b, v184
	v_mul_f32_e32 v188, v184, v184
	v_pk_mul_f32 v[190:191], v[12:13], v[186:187] op_sel_hi:[1,0]
	v_pk_mul_f32 v[192:193], v[14:15], v[186:187] op_sel_hi:[1,0]
	v_pk_mul_f32 v[12:13], v[12:13], v[8:9]
	v_exp_f32_e32 v190, v190
	v_exp_f32_e32 v191, v191
	v_exp_f32_e32 v192, v192
	v_exp_f32_e32 v193, v193
	v_pk_mul_f32 v[14:15], v[14:15], v[10:11]
	v_pk_add_f32 v[190:191], v[190:191], v[182:183] op_sel_hi:[1,0]
	v_pk_add_f32 v[192:193], v[192:193], v[182:183] op_sel_hi:[1,0]
	v_pk_mul_f32 v[12:13], v[12:13], v[188:189] op_sel_hi:[1,0]
	v_rcp_f32_e32 v190, v190
	v_rcp_f32_e32 v191, v191
	v_rcp_f32_e32 v192, v192
	v_rcp_f32_e32 v193, v193
	v_pk_mul_f32 v[14:15], v[14:15], v[188:189] op_sel_hi:[1,0]
	v_pk_mul_f32 v[12:13], v[12:13], v[190:191]
	v_pk_mul_f32 v[14:15], v[14:15], v[192:193]
	v_pk_mul_f32 v[190:191], v[4:5], v[186:187] op_sel_hi:[1,0]
	v_pk_mul_f32 v[192:193], v[6:7], v[186:187] op_sel_hi:[1,0]
	v_pk_mul_f32 v[4:5], v[4:5], v[0:1]
	v_exp_f32_e32 v190, v190
	v_exp_f32_e32 v191, v191
	v_exp_f32_e32 v192, v192
	v_exp_f32_e32 v193, v193
	v_pk_mul_f32 v[6:7], v[6:7], v[2:3]
	v_pk_add_f32 v[190:191], v[190:191], v[182:183] op_sel_hi:[1,0]
	v_pk_add_f32 v[192:193], v[192:193], v[182:183] op_sel_hi:[1,0]
	v_pk_mul_f32 v[4:5], v[4:5], v[188:189] op_sel_hi:[1,0]
	v_rcp_f32_e32 v190, v190
	v_rcp_f32_e32 v191, v191
	v_rcp_f32_e32 v192, v192
	v_rcp_f32_e32 v193, v193
	v_pk_mul_f32 v[6:7], v[6:7], v[188:189] op_sel_hi:[1,0]
	v_pk_mul_f32 v[4:5], v[4:5], v[190:191]
	v_pk_mul_f32 v[6:7], v[6:7], v[192:193]
	v_cvt_pk_bf16_f32 v198, v12, v13
	v_cvt_pk_bf16_f32 v199, v14, v15
	v_cvt_pk_bf16_f32 v200, v4, v5
	v_cvt_pk_bf16_f32 v201, v6, v7
	global_store_dwordx4 v[202:203], v[198:201], off
	s_cbranch_vccnz .LBB0_219
	s_and_b64 vcc, exec, s[10:11]
	s_cbranch_vccnz .LBB0_218
	s_barrier
	s_branch .LBB0_218

; __device__ __forceinline__ float rstd_of(float ss, float inv_n) { return __builtin_amdgcn_rsqf(ss * inv_n + 1e-6f); }
; __device__ __forceinline__ float sigmoid_f(float v) { return __builtin_amdgcn_rcpf(1.0f + __builtin_amdgcn_exp2f(-1.4426950408889634f * v)); }
; __device__ __forceinline__ u32x4 pack8(const f32x4 a, const f32x4 b) { u32x4 w; w.x = cvt_pk_bf16(a[0], a[1]); w.y = cvt_pk_bf16(a[2], a[3]); w.z = cvt_pk_bf16(b[0], b[1]); w.w = cvt_pk_bf16(b[2], b[3]); return w; }
;     __device__ __forceinline__ void operator()(f32x4 (&acc)[2][2][4][2], const Unit& u_, int wr, int wc, int fr, int fq) const {
;         Unit u = u_; if constexpr (OPQ) { unsigned o1_ = ~0u; asm volatile("" : "+s"(u.pm), "+s"(u.pn), "+s"(o1_)); const int l_ = (int)__builtin_amdgcn_mbcnt_hi(o1_, __builtin_amdgcn_mbcnt_lo(o1_, 0u)); fr = l_ & 15; fq = l_ >> 4; }
;         const int row0 = u.pm * BM + wr * 64 + fr, col0 = u.pn * HALF + wc * 32 + 8 * fq;
; #pragma unroll
;         for (int ai = 0; ai < 2; ++ai)
; #pragma unroll
;             for (int m = 0; m < 4; ++m) {
;                 const int row = row0 + ai * HALF + m * 16; const float r = rstd_of(sl[u.par * 256 + ai * HALF + wr * 64 + m * 16 + fr], 1.0f / 2048.0f) * ascale;
;                 f32x4 o[2];
; #pragma unroll
;                 for (int n = 0; n < 2; ++n) { const f32x4 g = acc[ai][0][m][n] * r, uu = acc[ai][1][m][n] * r;
; #pragma unroll
;                     for (int e = 0; e < 4; ++e) o[n][e] = g[e] * uu[e] * sigmoid_f(g[e]); }
;                 if constexpr (F8OUT) {
;                     typedef unsigned u32x2 __attribute__((ext_vector_type(2))); u32x2 w8; w8.x = pack4_fp8(o[0][0] * F8_ACT_SCALE, o[0][1] * F8_ACT_SCALE, o[0][2] * F8_ACT_SCALE, o[0][3] * F8_ACT_SCALE);
;                     w8.y = pack4_fp8(o[1][0] * F8_ACT_SCALE, o[1][1] * F8_ACT_SCALE, o[1][2] * F8_ACT_SCALE, o[1][3] * F8_ACT_SCALE);
;                     *(u32x2*)((unsigned char*)O + (((size_t)u.pm * (ldo / 128) + (col0 >> 7)) * BM + (ai * HALF + wr * 64 + m * 16 + fr)) * 128 + (col0 & 127)) = w8;
;                 } else
;                 *(u32x4*)(O + (((size_t)u.pm * (ldo / 64) + (col0 >> 6)) * BM + (ai * HALF + wr * 64 + m * 16 + fr)) * 64 + (col0 & 63)) = pack8(o[0], o[1]);
;             }
;     }
.LBB0_815:
	s_lshl_b32 s11, s65, 10
	v_mbcnt_lo_u32_b32 v168, -1, 0
	v_mbcnt_hi_u32_b32 v168, -1, v168
	s_add_i32 s11, s53, s11
	v_and_b32_e32 v169, 15, v168
	v_lshl_add_u32 v166, v169, 2, s11
	ds_read_b32 v172, v166
	ds_read_b32 v173, v166 offset:64
	ds_read_b32 v174, v166 offset:128
	ds_read_b32 v175, v166 offset:192
	ds_read_b32 v176, v166 offset:512
	ds_read_b32 v177, v166 offset:576
	ds_read_b32 v178, v166 offset:640
	ds_read_b32 v179, v166 offset:704
	s_lshl_b32 s10, s52, 7
	v_lshrrev_b32_e32 v168, 1, v168
	s_or_b32 s10, s10, s91
	v_and_b32_e32 v168, 56, v168
	v_add_u32_e32 v167, s10, v168
	s_andn2_b64 vcc, exec, s[8:9]
	s_mov_b64 s[8:9], -1
	v_or_b32_e32 v170, s94, v169
	v_mov_b32_e32 v171, 0
	v_ashrrev_i32_e32 v168, 6, v167
	v_ashrrev_i32_e32 v169, 31, v168
	v_mad_i64_i32 v[180:181], s[10:11], s50, v146, v[168:169]
	v_lshlrev_b64 v[170:171], 7, v[170:171]
	v_lshlrev_b64 v[180:181], 15, v[180:181]
	v_and_b32_e32 v168, 56, v167
	v_lshl_add_u64 v[180:181], s[34:35], 0, v[180:181]
	v_lshlrev_b32_e32 v168, 1, v168
	v_mov_b32_e32 v169, 0
	v_lshl_add_u64 v[180:181], v[180:181], 0, v[170:171]
	v_mov_b32_e32 v182, 1.0
	v_lshl_add_u64 v[180:181], v[180:181], 0, v[168:169]
	s_mov_b64 s[10:11], 0x1000
	v_lshl_add_u64 v[202:203], v[180:181], 0, s[10:11]
	s_mov_b64 s[10:11], 0x5000
	v_lshl_add_u64 v[204:205], v[180:181], 0, s[10:11]
	s_waitcnt lgkmcnt(0)
	v_fmamk_f32 v184, v172, 0x3a000000, v145
	v_rsq_f32_e32 v184, v184
	s_nop 0
	v_mul_f32_e32 v184, 0x3a800000, v184
	v_mul_f32_e32 v186, 0xbfb8aa3b, v184
	v_mul_f32_e32 v188, v184, v184
	v_pk_mul_f32 v[190:191], v[124:125], v[186:187] op_sel_hi:[1,0]
	v_pk_mul_f32 v[192:193], v[126:127], v[186:187] op_sel_hi:[1,0]
	v_pk_mul_f32 v[124:125], v[124:125], v[120:121]
	v_exp_f32_e32 v190, v190
	v_exp_f32_e32 v191, v191
	v_exp_f32_e32 v192, v192
	v_exp_f32_e32 v193, v193
	v_pk_mul_f32 v[126:127], v[126:127], v[122:123]
	v_pk_add_f32 v[190:191], v[190:191], v[182:183] op_sel_hi:[1,0]
	v_pk_add_f32 v[192:193], v[192:193], v[182:183] op_sel_hi:[1,0]
	v_pk_mul_f32 v[124:125], v[124:125], v[188:189] op_sel_hi:[1,0]
	v_rcp_f32_e32 v190, v190
	v_rcp_f32_e32 v191, v191
	v_rcp_f32_e32 v192, v192
	v_rcp_f32_e32 v193, v193
	v_pk_mul_f32 v[126:127], v[126:127], v[188:189] op_sel_hi:[1,0]
	v_pk_mul_f32 v[124:125], v[124:125], v[190:191]
	v_pk_mul_f32 v[126:127], v[126:127], v[192:193]
	v_pk_mul_f32 v[190:191], v[116:117], v[186:187] op_sel_hi:[1,0]
	v_pk_mul_f32 v[192:193], v[118:119], v[186:187] op_sel_hi:[1,0]
	v_pk_mul_f32 v[116:117], v[116:117], v[112:113]
	v_exp_f32_e32 v190, v190
	v_exp_f32_e32 v191, v191
	v_exp_f32_e32 v192, v192
	v_exp_f32_e32 v193, v193
	v_pk_mul_f32 v[118:119], v[118:119], v[114:115]
	v_pk_add_f32 v[190:191], v[190:191], v[182:183] op_sel_hi:[1,0]
	v_pk_add_f32 v[192:193], v[192:193], v[182:183] op_sel_hi:[1,0]
	v_pk_mul_f32 v[116:117], v[116:117], v[188:189] op_sel_hi:[1,0]
	v_rcp_f32_e32 v190, v190
	v_rcp_f32_e32 v191, v191
	v_rcp_f32_e32 v192, v192
	v_rcp_f32_e32 v193, v193
	v_pk_mul_f32 v[118:119], v[118:119], v[188:189] op_sel_hi:[1,0]
	v_pk_mul_f32 v[116:117], v[116:117], v[190:191]
	v_pk_mul_f32 v[118:119], v[118:119], v[192:193]
	v_cvt_pk_bf16_f32 v194, v124, v125
	v_cvt_pk_bf16_f32 v195, v126, v127
	v_cvt_pk_bf16_f32 v196, v116, v117
	v_cvt_pk_bf16_f32 v197, v118, v119
	global_store_dwordx4 v[202:203], v[194:197], off offset:-4096
	v_fmamk_f32 v184, v173, 0x3a000000, v145
	v_rsq_f32_e32 v184, v184
	s_nop 0
	v_mul_f32_e32 v184, 0x3a800000, v184
	v_mul_f32_e32 v186, 0xbfb8aa3b, v184
	v_mul_f32_e32 v188, v184, v184
	v_pk_mul_f32 v[190:191], v[108:109], v[186:187] op_sel_hi:[1,0]
	v_pk_mul_f32 v[192:193], v[110:111], v[186:187] op_sel_hi:[1,0]
	v_pk_mul_f32 v[108:109], v[108:109], v[104:105]
	v_exp_f32_e32 v190, v190
	v_exp_f32_e32 v191, v191
	v_exp_f32_e32 v192, v192
	v_exp_f32_e32 v193, v193
	v_pk_mul_f32 v[110:111], v[110:111], v[106:107]
	v_pk_add_f32 v[190:191], v[190:191], v[182:183] op_sel_hi:[1,0]
	v_pk_add_f32 v[192:193], v[192:193], v[182:183] op_sel_hi:[1,0]
	v_pk_mul_f32 v[108:109], v[108:109], v[188:189] op_sel_hi:[1,0]
	v_rcp_f32_e32 v190, v190
	v_rcp_f32_e32 v191, v191
	v_rcp_f32_e32 v192, v192
	v_rcp_f32_e32 v193, v193
	v_pk_mul_f32 v[110:111], v[110:111], v[188:189] op_sel_hi:[1,0]
	v_pk_mul_f32 v[108:109], v[108:109], v[190:191]
	v_pk_mul_f32 v[110:111], v[110:111], v[192:193]
	v_pk_mul_f32 v[190:191], v[100:101], v[186:187] op_sel_hi:[1,0]
	v_pk_mul_f32 v[192:193], v[102:103], v[186:187] op_sel_hi:[1,0]
	v_pk_mul_f32 v[100:101], v[100:101], v[96:97]
	v_exp_f32_e32 v190, v190
	v_exp_f32_e32 v191, v191
	v_exp_f32_e32 v192, v192
	v_exp_f32_e32 v193, v193
	v_pk_mul_f32 v[102:103], v[102:103], v[98:99]
	v_pk_add_f32 v[190:191], v[190:191], v[182:183] op_sel_hi:[1,0]
	v_pk_add_f32 v[192:193], v[192:193], v[182:183] op_sel_hi:[1,0]
	v_pk_mul_f32 v[100:101], v[100:101], v[188:189] op_sel_hi:[1,0]
	v_rcp_f32_e32 v190, v190
	v_rcp_f32_e32 v191, v191
	v_rcp_f32_e32 v192, v192
	v_rcp_f32_e32 v193, v193
	v_pk_mul_f32 v[102:103], v[102:103], v[188:189] op_sel_hi:[1,0]
	v_pk_mul_f32 v[100:101], v[100:101], v[190:191]
	v_pk_mul_f32 v[102:103], v[102:103], v[192:193]
	v_cvt_pk_bf16_f32 v198, v108, v109
	v_cvt_pk_bf16_f32 v199, v110, v111
	v_cvt_pk_bf16_f32 v200, v100, v101
	v_cvt_pk_bf16_f32 v201, v102, v103
	global_store_dwordx4 v[202:203], v[198:201], off offset:-2048
	v_fmamk_f32 v184, v174, 0x3a000000, v145
	v_rsq_f32_e32 v184, v184
	s_nop 0
	v_mul_f32_e32 v184, 0x3a800000, v184
	v_mul_f32_e32 v186, 0xbfb8aa3b, v184
	v_mul_f32_e32 v188, v184, v184
	v_pk_mul_f32 v[190:191], v[92:93], v[186:187] op_sel_hi:[1,0]
	v_pk_mul_f32 v[192:193], v[94:95], v[186:187] op_sel_hi:[1,0]
; __device__ __forceinline__ float rstd_of(float ss, float inv_n) { return __builtin_amdgcn_rsqf(ss * inv_n + 1e-6f); }
; __device__ __forceinline__ float sigmoid_f(float v) { return __builtin_amdgcn_rcpf(1.0f + __builtin_amdgcn_exp2f(-1.4426950408889634f * v)); }
; __device__ __forceinline__ u32x4 pack8(const f32x4 a, const f32x4 b) { u32x4 w; w.x = cvt_pk_bf16(a[0], a[1]); w.y = cvt_pk_bf16(a[2], a[3]); w.z = cvt_pk_bf16(b[0], b[1]); w.w = cvt_pk_bf16(b[2], b[3]); return w; }
;     __device__ __forceinline__ void operator()(f32x4 (&acc)[2][2][4][2], const Unit& u_, int wr, int wc, int fr, int fq) const {
;         Unit u = u_; if constexpr (OPQ) { unsigned o1_ = ~0u; asm volatile("" : "+s"(u.pm), "+s"(u.pn), "+s"(o1_)); const int l_ = (int)__builtin_amdgcn_mbcnt_hi(o1_, __builtin_amdgcn_mbcnt_lo(o1_, 0u)); fr = l_ & 15; fq = l_ >> 4; }
;         const int row0 = u.pm * BM + wr * 64 + fr, col0 = u.pn * HALF + wc * 32 + 8 * fq;
; #pragma unroll
;         for (int ai = 0; ai < 2; ++ai)
; #pragma unroll
;             for (int m = 0; m < 4; ++m) {
;                 const int row = row0 + ai * HALF + m * 16; const float r = rstd_of(sl[u.par * 256 + ai * HALF + wr * 64 + m * 16 + fr], 1.0f / 2048.0f) * ascale;
;                 f32x4 o[2];
; #pragma unroll
;                 for (int n = 0; n < 2; ++n) { const f32x4 g = acc[ai][0][m][n] * r, uu = acc[ai][1][m][n] * r;
; #pragma unroll
;                     for (int e = 0; e < 4; ++e) o[n][e] = g[e] * uu[e] * sigmoid_f(g[e]); }
;                 if constexpr (F8OUT) {
;                     typedef unsigned u32x2 __attribute__((ext_vector_type(2))); u32x2 w8; w8.x = pack4_fp8(o[0][0] * F8_ACT_SCALE, o[0][1] * F8_ACT_SCALE, o[0][2] * F8_ACT_SCALE, o[0][3] * F8_ACT_SCALE);
;                     w8.y = pack4_fp8(o[1][0] * F8_ACT_SCALE, o[1][1] * F8_ACT_SCALE, o[1][2] * F8_ACT_SCALE, o[1][3] * F8_ACT_SCALE);
;                     *(u32x2*)((unsigned char*)O + (((size_t)u.pm * (ldo / 128) + (col0 >> 7)) * BM + (ai * HALF + wr * 64 + m * 16 + fr)) * 128 + (col0 & 127)) = w8;
;                 } else
;                 *(u32x4*)(O + (((size_t)u.pm * (ldo / 64) + (col0 >> 6)) * BM + (ai * HALF + wr * 64 + m * 16 + fr)) * 64 + (col0 & 63)) = pack8(o[0], o[1]);
;             }
;     }
	v_pk_mul_f32 v[92:93], v[92:93], v[88:89]
	v_exp_f32_e32 v190, v190
	v_exp_f32_e32 v191, v191
	v_exp_f32_e32 v192, v192
	v_exp_f32_e32 v193, v193
	v_pk_mul_f32 v[94:95], v[94:95], v[90:91]
	v_pk_add_f32 v[190:191], v[190:191], v[182:183] op_sel_hi:[1,0]
	v_pk_add_f32 v[192:193], v[192:193], v[182:183] op_sel_hi:[1,0]
	v_pk_mul_f32 v[92:93], v[92:93], v[188:189] op_sel_hi:[1,0]
	v_rcp_f32_e32 v190, v190
	v_rcp_f32_e32 v191, v191
	v_rcp_f32_e32 v192, v192
	v_rcp_f32_e32 v193, v193
	v_pk_mul_f32 v[94:95], v[94:95], v[188:189] op_sel_hi:[1,0]
	v_pk_mul_f32 v[92:93], v[92:93], v[190:191]
	v_pk_mul_f32 v[94:95], v[94:95], v[192:193]
	v_pk_mul_f32 v[190:191], v[84:85], v[186:187] op_sel_hi:[1,0]
	v_pk_mul_f32 v[192:193], v[86:87], v[186:187] op_sel_hi:[1,0]
	v_pk_mul_f32 v[84:85], v[84:85], v[80:81]
	v_exp_f32_e32 v190, v190
	v_exp_f32_e32 v191, v191
	v_exp_f32_e32 v192, v192
	v_exp_f32_e32 v193, v193
	v_pk_mul_f32 v[86:87], v[86:87], v[82:83]
	v_pk_add_f32 v[190:191], v[190:191], v[182:183] op_sel_hi:[1,0]
	v_pk_add_f32 v[192:193], v[192:193], v[182:183] op_sel_hi:[1,0]
	v_pk_mul_f32 v[84:85], v[84:85], v[188:189] op_sel_hi:[1,0]
	v_rcp_f32_e32 v190, v190
	v_rcp_f32_e32 v191, v191
	v_rcp_f32_e32 v192, v192
	v_rcp_f32_e32 v193, v193
	v_pk_mul_f32 v[86:87], v[86:87], v[188:189] op_sel_hi:[1,0]
	v_pk_mul_f32 v[84:85], v[84:85], v[190:191]
	v_pk_mul_f32 v[86:87], v[86:87], v[192:193]
	v_cvt_pk_bf16_f32 v194, v92, v93
	v_cvt_pk_bf16_f32 v195, v94, v95
	v_cvt_pk_bf16_f32 v196, v84, v85
	v_cvt_pk_bf16_f32 v197, v86, v87
	global_store_dwordx4 v[202:203], v[194:197], off offset:0
	v_fmamk_f32 v184, v175, 0x3a000000, v145
	v_rsq_f32_e32 v184, v184
	s_nop 0
	v_mul_f32_e32 v184, 0x3a800000, v184
	v_mul_f32_e32 v186, 0xbfb8aa3b, v184
	v_mul_f32_e32 v188, v184, v184
	v_pk_mul_f32 v[190:191], v[76:77], v[186:187] op_sel_hi:[1,0]
	v_pk_mul_f32 v[192:193], v[78:79], v[186:187] op_sel_hi:[1,0]
	v_pk_mul_f32 v[76:77], v[76:77], v[72:73]
	v_exp_f32_e32 v190, v190
	v_exp_f32_e32 v191, v191
	v_exp_f32_e32 v192, v192
	v_exp_f32_e32 v193, v193
	v_pk_mul_f32 v[78:79], v[78:79], v[74:75]
	v_pk_add_f32 v[190:191], v[190:191], v[182:183] op_sel_hi:[1,0]
	v_pk_add_f32 v[192:193], v[192:193], v[182:183] op_sel_hi:[1,0]
	v_pk_mul_f32 v[76:77], v[76:77], v[188:189] op_sel_hi:[1,0]
	v_rcp_f32_e32 v190, v190
	v_rcp_f32_e32 v191, v191
	v_rcp_f32_e32 v192, v192
	v_rcp_f32_e32 v193, v193
	v_pk_mul_f32 v[78:79], v[78:79], v[188:189] op_sel_hi:[1,0]
	v_pk_mul_f32 v[76:77], v[76:77], v[190:191]
	v_pk_mul_f32 v[78:79], v[78:79], v[192:193]
	v_pk_mul_f32 v[190:191], v[68:69], v[186:187] op_sel_hi:[1,0]
	v_pk_mul_f32 v[192:193], v[70:71], v[186:187] op_sel_hi:[1,0]
	v_pk_mul_f32 v[68:69], v[68:69], v[64:65]
	v_exp_f32_e32 v190, v190
	v_exp_f32_e32 v191, v191
	v_exp_f32_e32 v192, v192
	v_exp_f32_e32 v193, v193
	v_pk_mul_f32 v[70:71], v[70:71], v[66:67]
	v_pk_add_f32 v[190:191], v[190:191], v[182:183] op_sel_hi:[1,0]
	v_pk_add_f32 v[192:193], v[192:193], v[182:183] op_sel_hi:[1,0]
	v_pk_mul_f32 v[68:69], v[68:69], v[188:189] op_sel_hi:[1,0]
	v_rcp_f32_e32 v190, v190
	v_rcp_f32_e32 v191, v191
	v_rcp_f32_e32 v192, v192
	v_rcp_f32_e32 v193, v193
	v_pk_mul_f32 v[70:71], v[70:71], v[188:189] op_sel_hi:[1,0]
	v_pk_mul_f32 v[68:69], v[68:69], v[190:191]
	v_pk_mul_f32 v[70:71], v[70:71], v[192:193]
	v_cvt_pk_bf16_f32 v198, v76, v77
	v_cvt_pk_bf16_f32 v199, v78, v79
	v_cvt_pk_bf16_f32 v200, v68, v69
	v_cvt_pk_bf16_f32 v201, v70, v71
	global_store_dwordx4 v[202:203], v[198:201], off offset:2048
	v_fmamk_f32 v184, v176, 0x3a000000, v145
	v_rsq_f32_e32 v184, v184
	s_nop 0
	v_mul_f32_e32 v184, 0x3a800000, v184
	v_mul_f32_e32 v186, 0xbfb8aa3b, v184
	v_mul_f32_e32 v188, v184, v184
	v_pk_mul_f32 v[190:191], v[60:61], v[186:187] op_sel_hi:[1,0]
	v_pk_mul_f32 v[192:193], v[62:63], v[186:187] op_sel_hi:[1,0]
	v_pk_mul_f32 v[60:61], v[60:61], v[56:57]
	v_exp_f32_e32 v190, v190
	v_exp_f32_e32 v191, v191
	v_exp_f32_e32 v192, v192
	v_exp_f32_e32 v193, v193
	v_pk_mul_f32 v[62:63], v[62:63], v[58:59]
	v_pk_add_f32 v[190:191], v[190:191], v[182:183] op_sel_hi:[1,0]
	v_pk_add_f32 v[192:193], v[192:193], v[182:183] op_sel_hi:[1,0]
	v_pk_mul_f32 v[60:61], v[60:61], v[188:189] op_sel_hi:[1,0]
	v_rcp_f32_e32 v190, v190
	v_rcp_f32_e32 v191, v191
	v_rcp_f32_e32 v192, v192
	v_rcp_f32_e32 v193, v193
	v_pk_mul_f32 v[62:63], v[62:63], v[188:189] op_sel_hi:[1,0]
	v_pk_mul_f32 v[60:61], v[60:61], v[190:191]
	v_pk_mul_f32 v[62:63], v[62:63], v[192:193]
	v_pk_mul_f32 v[190:191], v[52:53], v[186:187] op_sel_hi:[1,0]
	v_pk_mul_f32 v[192:193], v[54:55], v[186:187] op_sel_hi:[1,0]
	v_pk_mul_f32 v[52:53], v[52:53], v[48:49]
	v_exp_f32_e32 v190, v190
	v_exp_f32_e32 v191, v191
	v_exp_f32_e32 v192, v192
	v_exp_f32_e32 v193, v193
	v_pk_mul_f32 v[54:55], v[54:55], v[50:51]
	v_pk_add_f32 v[190:191], v[190:191], v[182:183] op_sel_hi:[1,0]
	v_pk_add_f32 v[192:193], v[192:193], v[182:183] op_sel_hi:[1,0]
	v_pk_mul_f32 v[52:53], v[52:53], v[188:189] op_sel_hi:[1,0]
	v_rcp_f32_e32 v190, v190
	v_rcp_f32_e32 v191, v191
	v_rcp_f32_e32 v192, v192
	v_rcp_f32_e32 v193, v193
	v_pk_mul_f32 v[54:55], v[54:55], v[188:189] op_sel_hi:[1,0]
	v_pk_mul_f32 v[52:53], v[52:53], v[190:191]
	v_pk_mul_f32 v[54:55], v[54:55], v[192:193]
	v_cvt_pk_bf16_f32 v194, v60, v61
	v_cvt_pk_bf16_f32 v195, v62, v63
	v_cvt_pk_bf16_f32 v196, v52, v53
	v_cvt_pk_bf16_f32 v197, v54, v55
	global_store_dwordx4 v[204:205], v[194:197], off offset:-4096
	v_fmamk_f32 v184, v177, 0x3a000000, v145
	v_rsq_f32_e32 v184, v184
	s_nop 0
	v_mul_f32_e32 v184, 0x3a800000, v184
	v_mul_f32_e32 v186, 0xbfb8aa3b, v184
	v_mul_f32_e32 v188, v184, v184
; __device__ __forceinline__ float rstd_of(float ss, float inv_n) { return __builtin_amdgcn_rsqf(ss * inv_n + 1e-6f); }
; __device__ __forceinline__ float sigmoid_f(float v) { return __builtin_amdgcn_rcpf(1.0f + __builtin_amdgcn_exp2f(-1.4426950408889634f * v)); }
; __device__ __forceinline__ u32x4 pack8(const f32x4 a, const f32x4 b) { u32x4 w; w.x = cvt_pk_bf16(a[0], a[1]); w.y = cvt_pk_bf16(a[2], a[3]); w.z = cvt_pk_bf16(b[0], b[1]); w.w = cvt_pk_bf16(b[2], b[3]); return w; }
;     __device__ __forceinline__ void operator()(f32x4 (&acc)[2][2][4][2], const Unit& u_, int wr, int wc, int fr, int fq) const {
;         Unit u = u_; if constexpr (OPQ) { unsigned o1_ = ~0u; asm volatile("" : "+s"(u.pm), "+s"(u.pn), "+s"(o1_)); const int l_ = (int)__builtin_amdgcn_mbcnt_hi(o1_, __builtin_amdgcn_mbcnt_lo(o1_, 0u)); fr = l_ & 15; fq = l_ >> 4; }
;         const int row0 = u.pm * BM + wr * 64 + fr, col0 = u.pn * HALF + wc * 32 + 8 * fq;
; #pragma unroll
;         for (int ai = 0; ai < 2; ++ai)
; #pragma unroll
;             for (int m = 0; m < 4; ++m) {
;                 const int row = row0 + ai * HALF + m * 16; const float r = rstd_of(sl[u.par * 256 + ai * HALF + wr * 64 + m * 16 + fr], 1.0f / 2048.0f) * ascale;
;                 f32x4 o[2];
; #pragma unroll
;                 for (int n = 0; n < 2; ++n) { const f32x4 g = acc[ai][0][m][n] * r, uu = acc[ai][1][m][n] * r;
; #pragma unroll
;                     for (int e = 0; e < 4; ++e) o[n][e] = g[e] * uu[e] * sigmoid_f(g[e]); }
;                 if constexpr (F8OUT) {
;                     typedef unsigned u32x2 __attribute__((ext_vector_type(2))); u32x2 w8; w8.x = pack4_fp8(o[0][0] * F8_ACT_SCALE, o[0][1] * F8_ACT_SCALE, o[0][2] * F8_ACT_SCALE, o[0][3] * F8_ACT_SCALE);
;                     w8.y = pack4_fp8(o[1][0] * F8_ACT_SCALE, o[1][1] * F8_ACT_SCALE, o[1][2] * F8_ACT_SCALE, o[1][3] * F8_ACT_SCALE);
;                     *(u32x2*)((unsigned char*)O + (((size_t)u.pm * (ldo / 128) + (col0 >> 7)) * BM + (ai * HALF + wr * 64 + m * 16 + fr)) * 128 + (col0 & 127)) = w8;
;                 } else
;                 *(u32x4*)(O + (((size_t)u.pm * (ldo / 64) + (col0 >> 6)) * BM + (ai * HALF + wr * 64 + m * 16 + fr)) * 64 + (col0 & 63)) = pack8(o[0], o[1]);
;             }
;     }
	v_pk_mul_f32 v[190:191], v[44:45], v[186:187] op_sel_hi:[1,0]
	v_pk_mul_f32 v[192:193], v[46:47], v[186:187] op_sel_hi:[1,0]
	v_pk_mul_f32 v[44:45], v[44:45], v[40:41]
	v_exp_f32_e32 v190, v190
	v_exp_f32_e32 v191, v191
	v_exp_f32_e32 v192, v192
	v_exp_f32_e32 v193, v193
	v_pk_mul_f32 v[46:47], v[46:47], v[42:43]
	v_pk_add_f32 v[190:191], v[190:191], v[182:183] op_sel_hi:[1,0]
	v_pk_add_f32 v[192:193], v[192:193], v[182:183] op_sel_hi:[1,0]
	v_pk_mul_f32 v[44:45], v[44:45], v[188:189] op_sel_hi:[1,0]
	v_rcp_f32_e32 v190, v190
	v_rcp_f32_e32 v191, v191
	v_rcp_f32_e32 v192, v192
	v_rcp_f32_e32 v193, v193
	v_pk_mul_f32 v[46:47], v[46:47], v[188:189] op_sel_hi:[1,0]
	v_pk_mul_f32 v[44:45], v[44:45], v[190:191]
	v_pk_mul_f32 v[46:47], v[46:47], v[192:193]
	v_pk_mul_f32 v[190:191], v[36:37], v[186:187] op_sel_hi:[1,0]
	v_pk_mul_f32 v[192:193], v[38:39], v[186:187] op_sel_hi:[1,0]
	v_pk_mul_f32 v[36:37], v[36:37], v[32:33]
	v_exp_f32_e32 v190, v190
	v_exp_f32_e32 v191, v191
	v_exp_f32_e32 v192, v192
	v_exp_f32_e32 v193, v193
	v_pk_mul_f32 v[38:39], v[38:39], v[34:35]
	v_pk_add_f32 v[190:191], v[190:191], v[182:183] op_sel_hi:[1,0]
	v_pk_add_f32 v[192:193], v[192:193], v[182:183] op_sel_hi:[1,0]
	v_pk_mul_f32 v[36:37], v[36:37], v[188:189] op_sel_hi:[1,0]
	v_rcp_f32_e32 v190, v190
	v_rcp_f32_e32 v191, v191
	v_rcp_f32_e32 v192, v192
	v_rcp_f32_e32 v193, v193
	v_pk_mul_f32 v[38:39], v[38:39], v[188:189] op_sel_hi:[1,0]
	v_pk_mul_f32 v[36:37], v[36:37], v[190:191]
	v_pk_mul_f32 v[38:39], v[38:39], v[192:193]
	v_cvt_pk_bf16_f32 v198, v44, v45
	v_cvt_pk_bf16_f32 v199, v46, v47
	v_cvt_pk_bf16_f32 v200, v36, v37
	v_cvt_pk_bf16_f32 v201, v38, v39
	global_store_dwordx4 v[204:205], v[198:201], off offset:-2048
	v_fmamk_f32 v184, v178, 0x3a000000, v145
	v_rsq_f32_e32 v184, v184
	s_nop 0
	v_mul_f32_e32 v184, 0x3a800000, v184
	v_mul_f32_e32 v186, 0xbfb8aa3b, v184
	v_mul_f32_e32 v188, v184, v184
	v_pk_mul_f32 v[190:191], v[28:29], v[186:187] op_sel_hi:[1,0]
	v_pk_mul_f32 v[192:193], v[30:31], v[186:187] op_sel_hi:[1,0]
	v_pk_mul_f32 v[28:29], v[28:29], v[24:25]
	v_exp_f32_e32 v190, v190
	v_exp_f32_e32 v191, v191
	v_exp_f32_e32 v192, v192
	v_exp_f32_e32 v193, v193
	v_pk_mul_f32 v[30:31], v[30:31], v[26:27]
	v_pk_add_f32 v[190:191], v[190:191], v[182:183] op_sel_hi:[1,0]
	v_pk_add_f32 v[192:193], v[192:193], v[182:183] op_sel_hi:[1,0]
	v_pk_mul_f32 v[28:29], v[28:29], v[188:189] op_sel_hi:[1,0]
	v_rcp_f32_e32 v190, v190
	v_rcp_f32_e32 v191, v191
	v_rcp_f32_e32 v192, v192
	v_rcp_f32_e32 v193, v193
	v_pk_mul_f32 v[30:31], v[30:31], v[188:189] op_sel_hi:[1,0]
	v_pk_mul_f32 v[28:29], v[28:29], v[190:191]
	v_pk_mul_f32 v[30:31], v[30:31], v[192:193]
	v_pk_mul_f32 v[190:191], v[20:21], v[186:187] op_sel_hi:[1,0]
	v_pk_mul_f32 v[192:193], v[22:23], v[186:187] op_sel_hi:[1,0]
	v_pk_mul_f32 v[20:21], v[20:21], v[16:17]
	v_exp_f32_e32 v190, v190
	v_exp_f32_e32 v191, v191
	v_exp_f32_e32 v192, v192
	v_exp_f32_e32 v193, v193
	v_pk_mul_f32 v[22:23], v[22:23], v[18:19]
	v_pk_add_f32 v[190:191], v[190:191], v[182:183] op_sel_hi:[1,0]
	v_pk_add_f32 v[192:193], v[192:193], v[182:183] op_sel_hi:[1,0]
	v_pk_mul_f32 v[20:21], v[20:21], v[188:189] op_sel_hi:[1,0]
	v_rcp_f32_e32 v190, v190
	v_rcp_f32_e32 v191, v191
	v_rcp_f32_e32 v192, v192
	v_rcp_f32_e32 v193, v193
	v_pk_mul_f32 v[22:23], v[22:23], v[188:189] op_sel_hi:[1,0]
	v_pk_mul_f32 v[20:21], v[20:21], v[190:191]
	v_pk_mul_f32 v[22:23], v[22:23], v[192:193]
	v_cvt_pk_bf16_f32 v194, v28, v29
	v_cvt_pk_bf16_f32 v195, v30, v31
	v_cvt_pk_bf16_f32 v196, v20, v21
	v_cvt_pk_bf16_f32 v197, v22, v23
	global_store_dwordx4 v[204:205], v[194:197], off offset:0
	v_fmamk_f32 v184, v179, 0x3a000000, v145
	v_rsq_f32_e32 v184, v184
	s_nop 0
	v_mul_f32_e32 v184, 0x3a800000, v184
	v_mul_f32_e32 v186, 0xbfb8aa3b, v184
	v_mul_f32_e32 v188, v184, v184
	v_pk_mul_f32 v[190:191], v[12:13], v[186:187] op_sel_hi:[1,0]
	v_pk_mul_f32 v[192:193], v[14:15], v[186:187] op_sel_hi:[1,0]
	v_pk_mul_f32 v[12:13], v[12:13], v[8:9]
	v_exp_f32_e32 v190, v190
	v_exp_f32_e32 v191, v191
	v_exp_f32_e32 v192, v192
	v_exp_f32_e32 v193, v193
	v_pk_mul_f32 v[14:15], v[14:15], v[10:11]
	v_pk_add_f32 v[190:191], v[190:191], v[182:183] op_sel_hi:[1,0]
	v_pk_add_f32 v[192:193], v[192:193], v[182:183] op_sel_hi:[1,0]
	v_pk_mul_f32 v[12:13], v[12:13], v[188:189] op_sel_hi:[1,0]
	v_rcp_f32_e32 v190, v190
	v_rcp_f32_e32 v191, v191
	v_rcp_f32_e32 v192, v192
	v_rcp_f32_e32 v193, v193
	v_pk_mul_f32 v[14:15], v[14:15], v[188:189] op_sel_hi:[1,0]
	v_pk_mul_f32 v[12:13], v[12:13], v[190:191]
	v_pk_mul_f32 v[14:15], v[14:15], v[192:193]
	v_pk_mul_f32 v[190:191], v[4:5], v[186:187] op_sel_hi:[1,0]
	v_pk_mul_f32 v[192:193], v[6:7], v[186:187] op_sel_hi:[1,0]
	v_pk_mul_f32 v[4:5], v[4:5], v[0:1]
	v_exp_f32_e32 v190, v190
	v_exp_f32_e32 v191, v191
	v_exp_f32_e32 v192, v192
	v_exp_f32_e32 v193, v193
	v_pk_mul_f32 v[6:7], v[6:7], v[2:3]
	v_pk_add_f32 v[190:191], v[190:191], v[182:183] op_sel_hi:[1,0]
	v_pk_add_f32 v[192:193], v[192:193], v[182:183] op_sel_hi:[1,0]
	v_pk_mul_f32 v[4:5], v[4:5], v[188:189] op_sel_hi:[1,0]
	v_rcp_f32_e32 v190, v190
	v_rcp_f32_e32 v191, v191
	v_rcp_f32_e32 v192, v192
	v_rcp_f32_e32 v193, v193
	v_pk_mul_f32 v[6:7], v[6:7], v[188:189] op_sel_hi:[1,0]
	v_pk_mul_f32 v[4:5], v[4:5], v[190:191]
	v_pk_mul_f32 v[6:7], v[6:7], v[192:193]
	v_cvt_pk_bf16_f32 v198, v12, v13
	v_cvt_pk_bf16_f32 v199, v14, v15
	v_cvt_pk_bf16_f32 v200, v4, v5
	v_cvt_pk_bf16_f32 v201, v6, v7
	global_store_dwordx4 v[204:205], v[198:201], off offset:2048
	s_cbranch_vccnz .LBB0_806
	s_and_b64 vcc, exec, s[16:17]
	s_cbranch_vccnz .LBB0_805
	s_barrier
	s_branch .LBB0_805
